# r44 + gdn_pre step 2b (UW *= beta, K*beta*eg) loop fully unrolled x8 with 2-deep LDS read prefetch, one bet read per row
# speedup vs baseline: 1.0092x; 1.0092x over previous
.LBB0_319:
	v_ashrrev_i32_e32 v3, 6, v2
	v_lshl_add_u32 v8, v3, 2, 0
	v_add_u32_e32 v9, 0x1da30, v8
	v_mad_u64_u32 v[4:5], s[44:45], v3, s64, v[52:53]
	v_mad_u64_u32 v[6:7], s[44:45], v3, s79, v[42:43]
	v_add_u32_e32 v197, 0x1db30, v8
	s_movk_i32 s44, 0xdff
	ds_read_b32 v198, v9
	ds_read_b32 v199, v4
	ds_read_b32 v200, v6 offset:17408
	ds_read_b32 v201, v197
	ds_read_b32 v202, v9 offset:32
	ds_read_b32 v203, v4 offset:4224
	ds_read_b32 v204, v6 offset:19584
	ds_read_b32 v205, v197 offset:32
	s_waitcnt lgkmcnt(4)
	ds_read_b32 v206, v9 offset:64
	ds_read_b32 v207, v4 offset:8448
	ds_read_b32 v208, v6 offset:21760
	ds_read_b32 v209, v197 offset:64
	v_mul_f32_e32 v210, v198, v199
	ds_write_b32 v4, v210
	v_mul_f32_e32 v211, v200, v198
	v_mul_f32_e32 v211, v211, v201
	ds_write_b32 v4, v211 offset:256
	s_waitcnt lgkmcnt(6)
	ds_read_b32 v198, v9 offset:96
	ds_read_b32 v199, v4 offset:12672
	ds_read_b32 v200, v6 offset:23936
	ds_read_b32 v201, v197 offset:96
	v_mul_f32_e32 v212, v202, v203
	ds_write_b32 v4, v212 offset:4224
	v_mul_f32_e32 v213, v204, v202
	v_mul_f32_e32 v213, v213, v205
	ds_write_b32 v4, v213 offset:4480
	s_waitcnt lgkmcnt(8)
	ds_read_b32 v202, v9 offset:128
	ds_read_b32 v203, v4 offset:16896
	ds_read_b32 v204, v6 offset:26112
	ds_read_b32 v205, v197 offset:128
	v_mul_f32_e32 v210, v206, v207
	ds_write_b32 v4, v210 offset:8448
	v_mul_f32_e32 v211, v208, v206
	v_mul_f32_e32 v211, v211, v209
	ds_write_b32 v4, v211 offset:8704
	s_waitcnt lgkmcnt(8)
	ds_read_b32 v206, v9 offset:160
	ds_read_b32 v207, v4 offset:21120
	ds_read_b32 v208, v6 offset:28288
	ds_read_b32 v209, v197 offset:160
	v_mul_f32_e32 v212, v198, v199
	ds_write_b32 v4, v212 offset:12672
	v_mul_f32_e32 v213, v200, v198
	v_mul_f32_e32 v213, v213, v201
	ds_write_b32 v4, v213 offset:12928
	s_waitcnt lgkmcnt(8)
	ds_read_b32 v198, v9 offset:192
	ds_read_b32 v199, v4 offset:25344
	ds_read_b32 v200, v6 offset:30464
	ds_read_b32 v201, v197 offset:192
	v_mul_f32_e32 v210, v202, v203
	ds_write_b32 v4, v210 offset:16896
	v_mul_f32_e32 v211, v204, v202
	v_mul_f32_e32 v211, v211, v205
	ds_write_b32 v4, v211 offset:17152
	s_waitcnt lgkmcnt(8)
	ds_read_b32 v202, v9 offset:224
	ds_read_b32 v203, v4 offset:29568
	ds_read_b32 v204, v6 offset:32640
	ds_read_b32 v205, v197 offset:224
	v_mul_f32_e32 v212, v206, v207
	ds_write_b32 v4, v212 offset:21120
	v_mul_f32_e32 v213, v208, v206
	v_mul_f32_e32 v213, v213, v209
	ds_write_b32 v4, v213 offset:21376
	s_waitcnt lgkmcnt(8)
	v_mul_f32_e32 v210, v198, v199
	ds_write_b32 v4, v210 offset:25344
	v_mul_f32_e32 v211, v200, v198
	v_mul_f32_e32 v211, v211, v201
	ds_write_b32 v4, v211 offset:25600
	s_waitcnt lgkmcnt(4)
	v_mul_f32_e32 v212, v202, v203
	ds_write_b32 v4, v212 offset:29568
	v_mul_f32_e32 v213, v204, v202
	v_mul_f32_e32 v213, v213, v205
	ds_write_b32 v4, v213 offset:29824
